# neighbourhood attention bias hook: exec-masked branches per element replaced by unconditional fma + v_cndmask with the same lane mask
# baseline (speedup 1.0000x reference)
; #define SLOAD(i, k0) do { sr_[i].vs0 = *reinterpret_cast<const bf16x8*>(&Vh[(long)((k0) + sr) * LDP + sc]); sr_[i].vs1 = *reinterpret_cast<const bf16x8*>(&Vh[(long)((k0) + 32 + sr) * LDP + sc]); \
;     sr_[i].ks0 = *reinterpret_cast<const bf16x8*>(&Kh[(long)((k0) + ksr) * LDP + ksc]); if (DK == 128) sr_[i].ks1 = *reinterpret_cast<const bf16x8*>(&Kh[(long)((k0) + 32 + ksr) * LDP + ksc]); } while (0)
; #define SWAIT() do { if (SD == 1) asm volatile("s_waitcnt vmcnt(0)" ::: "memory"); else if (DK == 128) asm volatile("s_waitcnt vmcnt(4)" ::: "memory"); else asm volatile("s_waitcnt vmcnt(3)" ::: "memory"); } while (0)
; #define HOOK(P0, P1, j) do { if (NA) na_hook(P0, P1, krow0 + (j), q_row, q_col, win_r, win_c, rpb, inv_scale, hi); } while (0)
; __device__ __forceinline__ void partialSM(f32x16& p0, f32x16& p1, float& m_reg, float& mn, float& alpha, float C, float thrRaw) {
;   float pmax = p0[0];
; #pragma unroll
;   for (int r = 1; r < 16; ++r) pmax = fmaxf(pmax, p0[r]);
; #pragma unroll
;   for (int r = 0; r < 16; ++r) pmax = fmaxf(pmax, p1[r]);
;   { auto rr = __builtin_amdgcn_permlane32_swap(__float_as_uint(pmax), __float_as_uint(pmax), false, false);
;     pmax = fmaxf(__uint_as_float(rr[0]), __uint_as_float(rr[1])); }
;   if (__builtin_expect(__all(pmax - m_reg <= thrRaw), 1)) { mn = m_reg; alpha = 1.f; }
;   else { mn = fmaxf(m_reg, pmax); alpha = __builtin_amdgcn_exp2f((m_reg - mn) * C); m_reg = mn; }
;   float mnC = -mn * C;
; #pragma unroll
;   for (int r = 0; r < 16; ++r) p0[r] = fmaf(p0[r], C, mnC);
; #pragma unroll
;   for (int r = 0; r < 16; ++r) p1[r] = fmaf(p1[r], C, mnC);
; #pragma unroll
;   for (int r = 0; r < 16; ++r) p0[r] = __builtin_amdgcn_exp2f(p0[r]);
; template <int DK, bool NA, bool QL, int SD> ...
;     ...
;   SLOAD(SE, 0); asm volatile("s_waitcnt vmcnt(0)" ::: "memory"); SWRITE(0, SE); __syncthreads();
;   qkt<DK, QL>(pA0, pA1, K_lds, qr, ql, r32, hi); HOOK(pA0, pA1, 0); partialSM(pA0, pA1, m_reg, mnA, alA, C, thrRaw);
;   SLOAD(SO, KVBLK); if (SD == 2) { if (2 < NT) SLOAD(SE, 2 * KVBLK); }
;   SWAIT(); SWRITE(1, SO); __syncthreads();
.LBB0_446:
	s_andn2_saveexec_b64 s[36:37], s[36:37]
	v_min_i32_e32 v236, 0xffffffd4, v41
	v_mov_b32_e32 v15, 0xf149f2ca
	s_or_b64 exec, exec, s[36:37]
	v_and_b32_e32 v17, 0x3fffffc0, v36
	s_add_i32 s33, 0, 0x10000
	v_lshl_add_u32 v18, v17, 2, s33
	v_lshlrev_b32_e32 v17, 3, v38
	v_and_b32_e32 v19, 0xc0, v42
	v_lshlrev_b32_e32 v32, 1, v38
	v_and_or_b32 v19, v17, 24, v19
	v_and_b32_e32 v32, 32, v32
	v_and_b32_e32 v17, 0x100, v17
	v_or3_b32 v19, v19, v32, v17
	v_max_f32_e32 v17, v44, v44
	v_max_f32_e32 v32, v43, v43
	v_max_f32_e32 v17, v32, v17
	v_max3_f32 v17, v17, v45, v20
	v_max3_f32 v17, v17, v21, v22
	v_max3_f32 v17, v17, v23, v24
	v_max3_f32 v17, v17, v25, v26
	v_max3_f32 v17, v17, v27, v28
	v_max3_f32 v17, v17, v29, v30
	v_max3_f32 v17, v17, v31, v16
	v_max3_f32 v17, v17, v34, v35
	v_max3_f32 v17, v17, v2, v3
	v_max3_f32 v17, v17, v4, v5
	v_max3_f32 v17, v17, v6, v7
	v_max3_f32 v17, v17, v8, v9
	v_max3_f32 v17, v17, v10, v11
	v_max3_f32 v17, v17, v12, v13
	v_max3_f32 v17, v17, v14, v15
	v_mov_b32_e32 v32, v17
	s_nop 1
	v_permlane32_swap_b32_e32 v17, v32
	v_max_f32_e32 v32, v32, v32
	v_max_f32_e32 v17, v17, v17
	v_max_f32_e32 v17, v17, v32
	v_add_f32_e32 v32, 0x7149f2ca, v17
	s_mov_b32 s37, 0x42b504f3
	v_max_f32_e32 v17, 0xf149f2ca, v17
	v_cmp_ge_f32_e32 vcc, s37, v32
	v_sub_f32_e32 v32, 0xf149f2ca, v17
	v_mul_f32_e32 v32, 0x3e0293ee, v32
	s_cmp_lg_u32 0, -1
	v_exp_f32_e32 v32, v32
	s_cselect_b32 s36, 0, 0
	s_cmp_eq_u64 vcc, exec
	s_cselect_b64 vcc, -1, 0
	v_cndmask_b32_e32 v237, v17, v199, vcc
	v_cndmask_b32_e64 v239, v32, 1.0, vcc
	v_mul_f32_e32 v32, 0xbe0293ee, v237
	v_fmamk_f32 v33, v44, 0x3e0293ee, v32
	s_mov_b32 s48, 0x3e0293ee
	v_pk_fma_f32 v[142:143], v[2:3], s[48:49], v[32:33] op_sel_hi:[1,0,0]
	v_add_u32_e32 v2, 64, v39
	s_movk_i32 s37, 0x1400
	v_pk_fma_f32 v[130:131], v[14:15], s[48:49], v[32:33] op_sel_hi:[1,0,0]
	v_pk_fma_f32 v[132:133], v[12:13], s[48:49], v[32:33] op_sel_hi:[1,0,0]
	v_pk_fma_f32 v[134:135], v[10:11], s[48:49], v[32:33] op_sel_hi:[1,0,0]
	v_pk_fma_f32 v[136:137], v[8:9], s[48:49], v[32:33] op_sel_hi:[1,0,0]
	v_pk_fma_f32 v[138:139], v[6:7], s[48:49], v[32:33] op_sel_hi:[1,0,0]
	v_pk_fma_f32 v[140:141], v[4:5], s[48:49], v[32:33] op_sel_hi:[1,0,0]
	v_pk_fma_f32 v[144:145], v[34:35], s[48:49], v[32:33] op_sel_hi:[1,0,0]
	v_mad_i64_i32 v[2:3], s[48:49], v2, s37, 0
	v_add_u32_e32 v6, 0x60, v39
	v_or_b32_e32 v2, v2, v40
	v_readlane_b32 s50, v253, 4
	v_mad_i64_i32 v[6:7], s[48:49], v6, s37, 0
	v_lshlrev_b64 v[10:11], 1, v[2:3]
	v_readlane_b32 s51, v253, 5
	v_or_b32_e32 v6, v6, v40
	v_lshlrev_b64 v[14:15], 1, v[6:7]
	v_lshl_add_u64 v[2:3], s[50:51], 0, v[10:11]
	v_readlane_b32 s48, v253, 2
	global_load_dwordx4 v[2:5], v[2:3], off
	v_lshl_add_u64 v[6:7], s[50:51], 0, v[14:15]
	v_readlane_b32 s49, v253, 3
	global_load_dwordx4 v[6:9], v[6:7], off
	v_fmamk_f32 v17, v43, 0x3e0293ee, v32
	v_lshl_add_u64 v[10:11], s[48:49], 0, v[10:11]
	v_mov_b32_e32 v43, v32
	global_load_dwordx4 v[10:13], v[10:11], off
	v_lshl_add_u64 v[14:15], s[48:49], 0, v[14:15]
	v_fmac_f32_e32 v43, 0x3e0293ee, v16
	v_exp_f32_e32 v94, v17
	global_load_dwordx4 v[14:17], v[14:15], off
	v_add_u32_e32 v151, s36, v19
	s_addk_i32 s36, 0x4000
	v_add_u32_e32 v149, s36, v19
	s_movk_i32 s36, 0x2800
	v_fmamk_f32 v42, v45, 0x3e0293ee, v32
	v_fmamk_f32 v20, v20, 0x3e0293ee, v32
	v_fmamk_f32 v21, v21, 0x3e0293ee, v32
	v_fmamk_f32 v22, v22, 0x3e0293ee, v32
	v_fmamk_f32 v23, v23, 0x3e0293ee, v32
	v_fmamk_f32 v24, v24, 0x3e0293ee, v32
	v_fmamk_f32 v25, v25, 0x3e0293ee, v32
	v_fmamk_f32 v26, v26, 0x3e0293ee, v32
	v_fmamk_f32 v27, v27, 0x3e0293ee, v32
	v_fmamk_f32 v28, v28, 0x3e0293ee, v32
	v_fmamk_f32 v29, v29, 0x3e0293ee, v32
	v_fmamk_f32 v30, v30, 0x3e0293ee, v32
	v_fmamk_f32 v31, v31, 0x3e0293ee, v32
	s_waitcnt vmcnt(0)
	v_exp_f32_e32 v95, v33
	v_exp_f32_e32 v92, v42
	v_exp_f32_e32 v93, v20
	v_exp_f32_e32 v88, v21
	v_exp_f32_e32 v89, v22
	v_exp_f32_e32 v90, v23
	v_exp_f32_e32 v91, v24
	v_exp_f32_e32 v80, v25
	v_exp_f32_e32 v81, v26
	v_exp_f32_e32 v82, v27
	v_exp_f32_e32 v83, v28
	v_exp_f32_e32 v84, v29
	v_exp_f32_e32 v85, v30
	v_exp_f32_e32 v86, v31
	v_exp_f32_e32 v87, v43
	s_waitcnt vmcnt(3)
	ds_write_b128 v152, v[2:5] offset:16384
	s_waitcnt vmcnt(2)
	ds_write_b128 v153, v[6:9] offset:16384
	s_waitcnt vmcnt(1)
	ds_write_b128 v156, v[10:13] offset:49152
	s_waitcnt vmcnt(0)
	ds_write_b128 v157, v[14:17] offset:49152
	v_mad_i64_i32 v[2:3], s[36:37], v39, s36, 0
	v_lshl_add_u32 v146, v0, 2, v18
	v_and_b32_e32 v0, 15, v36
	v_readlane_b32 s36, v254, 28
	v_cmp_gt_u32_e64 s[48:49], 32, v38
	v_lshl_or_b32 v2, v0, 4, v2
	v_readlane_b32 s37, v254, 29
	v_mov_b32_e32 v14, v1
	v_mov_b32_e32 v15, v1
	v_max_i32_e32 v242, -15, v41
	v_min_i32_e32 v241, 0xffffffd7, v41
	v_min_i32_e32 v240, 0xffffffd6, v41
	v_min_i32_e32 v238, 0xffffffd5, v41
	v_writelane_b32 v255, s48, 58
	v_lshl_add_u32 v148, v37, 2, v18
	v_lshl_add_u64 v[128:129], s[36:37], 0, v[2:3]
	v_mov_b32_e32 v0, v1
	v_mov_b32_e32 v2, v1
	v_mov_b32_e32 v3, v1
	v_mov_b32_e32 v4, v1
	v_mov_b32_e32 v5, v1
	v_mov_b32_e32 v6, v1
	v_mov_b32_e32 v7, v1
	v_mov_b32_e32 v8, v1
	v_mov_b32_e32 v9, v1
	v_mov_b32_e32 v10, v1
	v_mov_b32_e32 v11, v1
	v_mov_b32_e32 v12, v1
	v_mov_b32_e32 v13, v1
	v_mov_b32_e32 v150, 0
	v_mov_b64_e32 v[30:31], v[14:15]
	v_mov_b64_e32 v[46:47], v[14:15]
	s_mov_b32 s33, -1
	v_writelane_b32 v255, s49, 59
	v_mov_b64_e32 v[28:29], v[12:13]
	v_mov_b64_e32 v[26:27], v[10:11]
	v_mov_b64_e32 v[24:25], v[8:9]
	v_mov_b64_e32 v[22:23], v[6:7]
	v_mov_b64_e32 v[20:21], v[4:5]
	v_mov_b64_e32 v[18:19], v[2:3]
	v_mov_b64_e32 v[16:17], v[0:1]
	v_mov_b64_e32 v[44:45], v[12:13]
	v_mov_b64_e32 v[42:43], v[10:11]
	v_mov_b64_e32 v[40:41], v[8:9]
	v_mov_b64_e32 v[38:39], v[6:7]
	v_mov_b64_e32 v[36:37], v[4:5]
	v_mov_b64_e32 v[34:35], v[2:3]
	v_mov_b64_e32 v[32:33], v[0:1]
	v_mov_b32_e32 v48, 0
	v_mov_b32_e32 v49, v150
	v_mov_b32_e32 v50, v150
	v_mov_b32_e32 v51, v150
	v_mov_b32_e32 v52, v150
	v_mov_b32_e32 v53, v150
	v_mov_b32_e32 v54, v150
	v_mov_b32_e32 v55, v150
	v_mov_b32_e32 v56, v150
	v_mov_b32_e32 v57, v150
	v_mov_b32_e32 v58, v150
	v_mov_b32_e32 v59, v150
	v_mov_b32_e32 v60, v150
	v_mov_b32_e32 v61, v150
	v_mov_b32_e32 v62, v150
	v_mov_b32_e32 v63, v150
	v_mov_b32_e32 v64, 0
	v_mov_b32_e32 v65, v150
	v_mov_b32_e32 v66, v150
	v_mov_b32_e32 v67, v150
	v_mov_b32_e32 v68, v150
	v_mov_b32_e32 v69, v150
	v_mov_b32_e32 v70, v150
	v_mov_b32_e32 v71, v150
	v_mov_b32_e32 v72, v150
	v_mov_b32_e32 v73, v150
	v_mov_b32_e32 v74, v150
	v_mov_b32_e32 v75, v150
	v_mov_b32_e32 v76, v150
	v_mov_b32_e32 v77, v150
	v_mov_b32_e32 v78, v150
	v_mov_b32_e32 v79, v150
	s_waitcnt lgkmcnt(0)
	s_barrier
	v_mov_b32_e32 v155, 0xf149f2ca
; __device__ __forceinline__ int crow(int r, int hi) { return (r & 3) + 8 * (r >> 2) + 4 * hi; }
; template <int DK, bool QL>
; __device__ __forceinline__ void qkt(f32x16& p0, f32x16& p1, const bf16* Ks, const bf16x8* qr, const char* ql, int r32, int hi) {
;   p0 = f32x16{}; p1 = f32x16{};
; #pragma unroll
;   for (int d0 = 0; d0 < DK / 16; ++d0) { int cb = (d0 * 16 + hi * 8) * 2;
;     const bf16x8 qv = QL ? *reinterpret_cast<const bf16x8*>(ql + d0 * 1024) : qr[d0];
;     bf16x8 b0 = *reinterpret_cast<const bf16x8*>((const char*)Ks + kswz<DK>(r32, cb));
;     bf16x8 b1 = *reinterpret_cast<const bf16x8*>((const char*)Ks + kswz<DK>(32 + r32, cb));
;     p0 = __builtin_amdgcn_mfma_f32_32x32x16_bf16(b0, qv, p0, 0, 0, 0);
;     p1 = __builtin_amdgcn_mfma_f32_32x32x16_bf16(b1, qv, p1, 0, 0, 0); }
; }
; __device__ __forceinline__ void na_hook(f32x16& p0, f32x16& p1, int kr, int q_row, int q_col, int win_r, int win_c, const float* rpb, float inv_scale, int hi) {
;   const bool rowok = (kr >= win_r) && (kr < win_r + 8);
;   int ir = kr - q_row + 7; ir = ir < 0 ? 0 : (ir > 14 ? 14 : ir);
;   const float* rp = rpb + ir * 31;
; #pragma unroll
;   for (int r = 0; r < 16; ++r) {
;     const int kc = crow(r, hi);
;     { const bool ok = rowok && kc >= win_c && kc < win_c + 16; int ic = kc - q_col + 15; ic = ic < 0 ? 0 : (ic > 30 ? 30 : ic);
;       p0[r] = ok ? fmaf(rp[ic], inv_scale, p0[r]) : -1e30f; }
;     { const int kc2 = kc + 32; const bool ok = rowok && kc2 >= win_c && kc2 < win_c + 16; int ic = kc2 - q_col + 15; ic = ic < 0 ? 0 : (ic > 30 ? 30 : ic);
;       p1[r] = ok ? fmaf(rp[ic], inv_scale, p1[r]) : -1e30f; }
;   }
.LBB0_449:
	ds_read_b128 v[2:5], v147
	ds_read_b128 v[6:9], v158 offset:49152
	ds_read_b128 v[10:13], v158 offset:57344
	ds_read_b128 v[164:167], v147 offset:1024
	ds_read_b128 v[168:171], v159 offset:49152
	ds_read_b128 v[172:175], v159 offset:57344
	v_readlane_b32 s36, v254, 26
	s_add_i32 s50, s36, s33
	s_add_i32 s48, s50, -2
	s_waitcnt lgkmcnt(4)
	v_mfma_f32_32x32x16_bf16 v[112:127], v[6:9], v[2:5], 0
	v_readlane_b32 s36, v255, 32
	s_cmp_lt_u32 s48, s36
	v_readlane_b32 s49, v255, 33
	s_cselect_b64 s[36:37], -1, 0
	s_cmp_ge_u32 s48, s49
	s_cselect_b64 s[48:49], -1, 0
	s_or_b64 s[36:37], s[36:37], s[48:49]
	s_waitcnt lgkmcnt(3)
	v_mfma_f32_32x32x16_bf16 v[96:111], v[10:13], v[2:5], 0
	ds_read_b128 v[2:5], v147 offset:2048
	ds_read_b128 v[6:9], v160 offset:49152
	ds_read_b128 v[10:13], v160 offset:57344
	v_readlane_b32 s48, v255, 48
	s_add_i32 s51, s48, s33
	s_add_i32 s48, s51, -2
	v_med3_i32 v0, s48, -7, 7
	s_movk_i32 s48, 0x7c
	v_mul_lo_u32 v0, v0, s48
	s_waitcnt lgkmcnt(4)
	v_mfma_f32_32x32x16_bf16 v[112:127], v[168:171], v[164:167], v[112:127]
	v_readlane_b32 s48, v255, 50
	v_add_u32_e32 v0, 0, v0
	v_readlane_b32 s49, v255, 51
	s_nor_b64 s[48:49], s[48:49], s[36:37]
	v_mov_b32_e32 v14, 0xf149f2ca
	s_waitcnt lgkmcnt(3)
	v_mfma_f32_32x32x16_bf16 v[96:111], v[172:175], v[164:167], v[96:111]
	ds_read_b128 v[164:167], v147 offset:3072
	ds_read_b128 v[168:171], v161 offset:49152
	ds_read_b128 v[172:175], v161 offset:57344
	s_waitcnt lgkmcnt(4)
	v_mfma_f32_32x32x16_bf16 v[112:127], v[6:9], v[2:5], v[112:127]
	s_waitcnt lgkmcnt(3)
	v_mfma_f32_32x32x16_bf16 v[96:111], v[10:13], v[2:5], v[96:111]
	ds_read_b128 v[2:5], v147 offset:4096
	ds_read_b128 v[6:9], v176 offset:49152
	ds_read_b128 v[10:13], v176 offset:57344
	s_waitcnt lgkmcnt(4)
	v_mfma_f32_32x32x16_bf16 v[112:127], v[168:171], v[164:167], v[112:127]
	s_waitcnt lgkmcnt(3)
	v_mfma_f32_32x32x16_bf16 v[96:111], v[172:175], v[164:167], v[96:111]
	ds_read_b128 v[164:167], v147 offset:5120
	ds_read_b128 v[168:171], v177 offset:49152
	ds_read_b128 v[172:175], v177 offset:57344
	s_waitcnt lgkmcnt(4)
	v_mfma_f32_32x32x16_bf16 v[112:127], v[6:9], v[2:5], v[112:127]
	s_waitcnt lgkmcnt(3)
	v_mfma_f32_32x32x16_bf16 v[96:111], v[10:13], v[2:5], v[96:111]
	ds_read_b128 v[2:5], v147 offset:6144
	ds_read_b128 v[6:9], v207 offset:49152
	ds_read_b128 v[10:13], v207 offset:57344
	s_waitcnt lgkmcnt(4)
	v_mfma_f32_32x32x16_bf16 v[112:127], v[168:171], v[164:167], v[112:127]
	s_waitcnt lgkmcnt(3)
	v_mfma_f32_32x32x16_bf16 v[96:111], v[172:175], v[164:167], v[96:111]
	ds_read_b128 v[164:167], v147 offset:7168
	ds_read_b128 v[168:171], v208 offset:49152
	ds_read_b128 v[172:175], v208 offset:57344
	s_waitcnt lgkmcnt(4)
	v_mfma_f32_32x32x16_bf16 v[112:127], v[6:9], v[2:5], v[112:127]
	s_waitcnt lgkmcnt(3)
	v_mfma_f32_32x32x16_bf16 v[96:111], v[10:13], v[2:5], v[96:111]
	s_waitcnt lgkmcnt(1)
	v_mfma_f32_32x32x16_bf16 v[112:127], v[168:171], v[164:167], v[112:127]
	s_waitcnt lgkmcnt(0)
	v_mfma_f32_32x32x16_bf16 v[96:111], v[172:175], v[164:167], v[96:111]
	v_add_u32_e32 v2, 0x10800, v0
	v_mov_b32_e32 v0, 0xf149f2ca
	v_lshl_add_u32 v162, v242, 2, v2
	ds_read_b32 v162, v162 offset:928
	v_lshl_add_u32 v178, v209, 2, v2
	ds_read_b32 v178, v178 offset:928
	v_lshl_add_u32 v179, v210, 2, v2
	ds_read_b32 v179, v179 offset:928
	v_lshl_add_u32 v180, v211, 2, v2
	ds_read_b32 v180, v180 offset:928
	v_lshl_add_u32 v201, v212, 2, v2
	ds_read_b32 v201, v201 offset:928
	v_lshl_add_u32 v202, v213, 2, v2
	ds_read_b32 v202, v202 offset:928
	v_lshl_add_u32 v168, v214, 2, v2
	ds_read_b32 v168, v168 offset:928
	v_lshl_add_u32 v169, v215, 2, v2
	ds_read_b32 v169, v169 offset:928
	v_lshl_add_u32 v170, v216, 2, v2
	ds_read_b32 v170, v170 offset:928
	v_lshl_add_u32 v171, v217, 2, v2
	ds_read_b32 v171, v171 offset:928
	v_lshl_add_u32 v190, v218, 2, v2
	ds_read_b32 v190, v190 offset:928
	v_lshl_add_u32 v191, v219, 2, v2
	ds_read_b32 v191, v191 offset:928
	v_lshl_add_u32 v193, v220, 2, v2
	ds_read_b32 v193, v193 offset:928
	v_lshl_add_u32 v194, v221, 2, v2
	ds_read_b32 v194, v194 offset:928
	v_lshl_add_u32 v195, v222, 2, v2
	ds_read_b32 v195, v195 offset:928
	v_lshl_add_u32 v196, v223, 2, v2
	ds_read_b32 v196, v196 offset:928
	s_waitcnt lgkmcnt(0)
	v_fmamk_f32 v162, v162, 0x413504f3, v112
	v_cndmask_b32_e64 v14, v155, v162, s[48:49]
.LBB0_451:
	s_xor_b64 vcc, s[36:37], -1
	s_mov_b64 s[54:55], s[52:53]
	s_and_b64 s[48:49], vcc, s[52:53]
	v_readlane_b32 s52, v255, 52
	v_readlane_b32 s53, v255, 53
	s_and_b64 s[52:53], s[48:49], s[52:53]
	v_fmamk_f32 v178, v178, 0x413504f3, v96
	v_cndmask_b32_e64 v0, v155, v178, s[52:53]
.LBB0_453:
	v_readlane_b32 s48, v255, 54
	v_readlane_b32 s49, v255, 55
	s_nor_b64 s[52:53], s[48:49], s[36:37]
	v_mov_b32_e32 v15, 0xf149f2ca
	v_mov_b32_e32 v96, 0xf149f2ca
	v_fmamk_f32 v179, v179, 0x413504f3, v113
	v_cndmask_b32_e64 v96, v155, v179, s[52:53]
.LBB0_455:
	v_readlane_b32 s48, v255, 56
	v_readlane_b32 s49, v255, 57
	s_and_b64 s[48:49], vcc, s[48:49]
	s_and_b64 s[52:53], s[48:49], s[56:57]
	v_fmamk_f32 v180, v180, 0x413504f3, v97
	v_cndmask_b32_e64 v15, v155, v180, s[52:53]
.LBB0_457:
	s_nor_b64 s[52:53], s[58:59], s[36:37]
	v_mov_b32_e32 v97, 0xf149f2ca
	v_mov_b32_e32 v243, 0xf149f2ca
	v_fmamk_f32 v201, v201, 0x413504f3, v114
	v_cndmask_b32_e64 v243, v155, v201, s[52:53]
.LBB0_459:
	s_and_b64 s[48:49], vcc, s[60:61]
	s_and_b64 s[52:53], s[48:49], s[62:63]
	v_fmamk_f32 v202, v202, 0x413504f3, v98
	v_cndmask_b32_e64 v97, v155, v202, s[52:53]
.LBB0_461:
	s_nor_b64 s[52:53], s[64:65], s[36:37]
	v_mov_b32_e32 v98, 0xf149f2ca
	v_mov_b32_e32 v244, 0xf149f2ca
	v_fmamk_f32 v168, v168, 0x413504f3, v115
	v_cndmask_b32_e64 v244, v155, v168, s[52:53]
; __device__ __forceinline__ int crow(int r, int hi) { return (r & 3) + 8 * (r >> 2) + 4 * hi; }
; __device__ __forceinline__ void na_hook(f32x16& p0, f32x16& p1, int kr, int q_row, int q_col, int win_r, int win_c, const float* rpb, float inv_scale, int hi) {
;   const bool rowok = (kr >= win_r) && (kr < win_r + 8);
;   int ir = kr - q_row + 7; ir = ir < 0 ? 0 : (ir > 14 ? 14 : ir);
;   const float* rp = rpb + ir * 31;
; #pragma unroll
;   for (int r = 0; r < 16; ++r) {
;     const int kc = crow(r, hi);
;     { const bool ok = rowok && kc >= win_c && kc < win_c + 16; int ic = kc - q_col + 15; ic = ic < 0 ? 0 : (ic > 30 ? 30 : ic);
;       p0[r] = ok ? fmaf(rp[ic], inv_scale, p0[r]) : -1e30f; }
;     { const int kc2 = kc + 32; const bool ok = rowok && kc2 >= win_c && kc2 < win_c + 16; int ic = kc2 - q_col + 15; ic = ic < 0 ? 0 : (ic > 30 ? 30 : ic);
;       p1[r] = ok ? fmaf(rp[ic], inv_scale, p1[r]) : -1e30f; }
;   }
; }
.LBB0_463:
	s_and_b64 s[48:49], vcc, s[66:67]
	s_and_b64 s[52:53], s[48:49], s[68:69]
	v_fmamk_f32 v169, v169, 0x413504f3, v99
	v_cndmask_b32_e64 v98, v155, v169, s[52:53]
.LBB0_465:
	s_nor_b64 s[52:53], s[70:71], s[36:37]
	v_mov_b32_e32 v99, 0xf149f2ca
	v_mov_b32_e32 v115, 0xf149f2ca
	v_fmamk_f32 v170, v170, 0x413504f3, v116
	v_cndmask_b32_e64 v115, v155, v170, s[52:53]
.LBB0_467:
	s_and_b64 s[48:49], vcc, s[72:73]
	s_and_b64 s[52:53], s[48:49], s[74:75]
	v_fmamk_f32 v171, v171, 0x413504f3, v100
	v_cndmask_b32_e64 v99, v155, v171, s[52:53]
.LBB0_469:
	s_nor_b64 s[52:53], s[76:77], s[36:37]
	v_mov_b32_e32 v100, 0xf149f2ca
	v_mov_b32_e32 v245, 0xf149f2ca
	v_fmamk_f32 v190, v190, 0x413504f3, v117
	v_cndmask_b32_e64 v245, v155, v190, s[52:53]
.LBB0_471:
	s_and_b64 s[48:49], vcc, s[78:79]
	s_and_b64 s[52:53], s[48:49], s[80:81]
	v_fmamk_f32 v191, v191, 0x413504f3, v101
	v_cndmask_b32_e64 v100, v155, v191, s[52:53]
.LBB0_473:
	s_nor_b64 s[52:53], s[82:83], s[36:37]
	v_mov_b32_e32 v101, 0xf149f2ca
	v_mov_b32_e32 v117, 0xf149f2ca
	v_fmamk_f32 v193, v193, 0x413504f3, v118
	v_cndmask_b32_e64 v117, v155, v193, s[52:53]
.LBB0_475:
	s_and_b64 s[48:49], vcc, s[84:85]
	s_and_b64 s[52:53], s[48:49], s[86:87]
	v_fmamk_f32 v194, v194, 0x413504f3, v102
	v_cndmask_b32_e64 v101, v155, v194, s[52:53]
.LBB0_477:
	s_nor_b64 s[52:53], s[88:89], s[36:37]
	v_mov_b32_e32 v102, 0xf149f2ca
	v_mov_b32_e32 v118, 0xf149f2ca
	v_fmamk_f32 v195, v195, 0x413504f3, v119
	v_cndmask_b32_e64 v118, v155, v195, s[52:53]
.LBB0_479:
	s_and_b64 s[48:49], vcc, s[90:91]
	s_and_b64 s[52:53], s[48:49], s[92:93]
	v_fmamk_f32 v196, v196, 0x413504f3, v103
	v_cndmask_b32_e64 v102, v155, v196, s[52:53]
.LBB0_481:
	v_lshl_add_u32 v162, v224, 2, v2
	ds_read_b32 v162, v162 offset:928
	v_lshl_add_u32 v178, v225, 2, v2
	ds_read_b32 v178, v178 offset:928
	v_lshl_add_u32 v179, v226, 2, v2
	ds_read_b32 v179, v179 offset:928
	v_lshl_add_u32 v180, v227, 2, v2
	ds_read_b32 v180, v180 offset:928
	v_lshl_add_u32 v201, v228, 2, v2
	ds_read_b32 v201, v201 offset:928
	v_lshl_add_u32 v202, v229, 2, v2
	ds_read_b32 v202, v202 offset:928
	v_lshl_add_u32 v168, v230, 2, v2
	ds_read_b32 v168, v168 offset:928
	v_lshl_add_u32 v169, v231, 2, v2
	ds_read_b32 v169, v169 offset:928
	v_lshl_add_u32 v170, v232, 2, v2
	ds_read_b32 v170, v170 offset:928
	v_lshl_add_u32 v171, v241, 2, v2
	ds_read_b32 v171, v171 offset:1152
	v_lshl_add_u32 v190, v233, 2, v2
	ds_read_b32 v190, v190 offset:928
	v_lshl_add_u32 v191, v240, 2, v2
	ds_read_b32 v191, v191 offset:1156
	v_lshl_add_u32 v193, v234, 2, v2
	ds_read_b32 v193, v193 offset:928
	v_lshl_add_u32 v194, v238, 2, v2
	ds_read_b32 v194, v194 offset:1160
	v_lshl_add_u32 v195, v235, 2, v2
	ds_read_b32 v195, v195 offset:928
	v_lshl_add_u32 v196, v236, 2, v2
	ds_read_b32 v196, v196 offset:1164
	s_nor_b64 s[52:53], s[46:47], s[36:37]
	v_mov_b32_e32 v103, 0xf149f2ca
	v_mov_b32_e32 v119, 0xf149f2ca
	s_waitcnt lgkmcnt(0)
	v_fmamk_f32 v162, v162, 0x413504f3, v120
	v_cndmask_b32_e64 v119, v155, v162, s[52:53]
.LBB0_483:
	s_and_b64 s[52:53], vcc, s[94:95]
	v_fmamk_f32 v178, v178, 0x413504f3, v104
	v_cndmask_b32_e64 v103, v155, v178, s[52:53]
.LBB0_485:
	s_or_b64 s[48:49], s[96:97], s[36:37]
	s_nor_b64 s[52:53], s[48:49], s[2:3]
	v_mov_b32_e32 v104, 0xf149f2ca
	v_mov_b32_e32 v120, 0xf149f2ca
	v_fmamk_f32 v179, v179, 0x413504f3, v121
	v_cndmask_b32_e64 v120, v155, v179, s[52:53]
.LBB0_487:
	s_and_b64 s[52:53], vcc, s[4:5]
	v_fmamk_f32 v180, v180, 0x413504f3, v105
	v_cndmask_b32_e64 v104, v155, v180, s[52:53]
.LBB0_489:
	s_or_b64 s[48:49], s[6:7], s[36:37]
	s_nor_b64 s[52:53], s[48:49], s[8:9]
	v_mov_b32_e32 v105, 0xf149f2ca
	v_mov_b32_e32 v121, 0xf149f2ca
	v_fmamk_f32 v201, v201, 0x413504f3, v122
	v_cndmask_b32_e64 v121, v155, v201, s[52:53]
.LBB0_491:
	s_and_b64 s[52:53], vcc, s[10:11]
	v_fmamk_f32 v202, v202, 0x413504f3, v106
	v_cndmask_b32_e64 v105, v155, v202, s[52:53]
.LBB0_493:
	s_or_b64 s[48:49], s[12:13], s[36:37]
	s_nor_b64 s[52:53], s[48:49], s[14:15]
	v_mov_b32_e32 v106, 0xf149f2ca
	v_mov_b32_e32 v122, 0xf149f2ca
	v_fmamk_f32 v168, v168, 0x413504f3, v123
	v_cndmask_b32_e64 v122, v155, v168, s[52:53]
.LBB0_495:
	s_and_b64 s[52:53], vcc, s[16:17]
	v_fmamk_f32 v169, v169, 0x413504f3, v107
	v_cndmask_b32_e64 v106, v155, v169, s[52:53]
.LBB0_497:
	s_or_b64 s[48:49], s[18:19], s[36:37]
	s_nor_b64 s[52:53], s[48:49], s[20:21]
	v_mov_b32_e32 v107, 0xf149f2ca
	v_mov_b32_e32 v123, 0xf149f2ca
	v_fmamk_f32 v170, v170, 0x413504f3, v124
	v_cndmask_b32_e64 v123, v155, v170, s[52:53]
.LBB0_499:
	s_nor_b64 s[52:53], s[36:37], s[22:23]
	v_fmamk_f32 v171, v171, 0x413504f3, v108
	v_cndmask_b32_e64 v107, v155, v171, s[52:53]
.LBB0_501:
	s_or_b64 s[48:49], s[24:25], s[36:37]
	s_nor_b64 s[52:53], s[48:49], s[26:27]
	v_mov_b32_e32 v108, 0xf149f2ca
	v_mov_b32_e32 v124, 0xf149f2ca
	v_fmamk_f32 v190, v190, 0x413504f3, v125
	v_cndmask_b32_e64 v124, v155, v190, s[52:53]
.LBB0_503:
	s_nor_b64 s[52:53], s[36:37], s[28:29]
	v_fmamk_f32 v191, v191, 0x413504f3, v109
	v_cndmask_b32_e64 v108, v155, v191, s[52:53]
.LBB0_505:
	s_or_b64 s[48:49], s[30:31], s[36:37]
	s_nor_b64 s[52:53], s[48:49], s[34:35]
	v_mov_b32_e32 v109, 0xf149f2ca
	v_mov_b32_e32 v125, 0xf149f2ca
	v_fmamk_f32 v193, v193, 0x413504f3, v126
	v_cndmask_b32_e64 v125, v155, v193, s[52:53]
.LBB0_507:
	s_nor_b64 s[52:53], s[36:37], s[42:43]
	v_fmamk_f32 v194, v194, 0x413504f3, v110
	v_cndmask_b32_e64 v109, v155, v194, s[52:53]
.LBB0_509:
	s_or_b64 s[48:49], s[0:1], s[36:37]
	s_nor_b64 s[48:49], s[48:49], s[40:41]
	v_mov_b32_e32 v110, 0xf149f2ca
	v_mov_b32_e32 v126, 0xf149f2ca
	s_and_saveexec_b64 vcc, s[48:49]
	s_cbranch_execz .LBB0_511
	v_fmac_f32_e32 v127, 0x413504f3, v195
	v_mov_b32_e32 v126, v127

; __device__ __forceinline__ int crow(int r, int hi) { return (r & 3) + 8 * (r >> 2) + 4 * hi; }
; __device__ __forceinline__ void partialSM(f32x16& p0, f32x16& p1, float& m_reg, float& mn, float& alpha, float C, float thrRaw) {
;     ...
;   float mnC = -mn * C;
; #pragma unroll
;   for (int r = 0; r < 16; ++r) p0[r] = fmaf(p0[r], C, mnC);
; #pragma unroll
;   for (int r = 0; r < 16; ++r) p1[r] = fmaf(p1[r], C, mnC);
; #pragma unroll
;   for (int r = 0; r < 16; ++r) p0[r] = __builtin_amdgcn_exp2f(p0[r]);
; template <int DK, bool QL>
; __device__ __forceinline__ void qkt(f32x16& p0, f32x16& p1, const bf16* Ks, const bf16x8* qr, const char* ql, int r32, int hi) {
;   p0 = f32x16{}; p1 = f32x16{};
; #pragma unroll
;   for (int d0 = 0; d0 < DK / 16; ++d0) { int cb = (d0 * 16 + hi * 8) * 2;
;     const bf16x8 qv = QL ? *reinterpret_cast<const bf16x8*>(ql + d0 * 1024) : qr[d0];
;     bf16x8 b0 = *reinterpret_cast<const bf16x8*>((const char*)Ks + kswz<DK>(r32, cb));
;     bf16x8 b1 = *reinterpret_cast<const bf16x8*>((const char*)Ks + kswz<DK>(32 + r32, cb));
;     p0 = __builtin_amdgcn_mfma_f32_32x32x16_bf16(b0, qv, p0, 0, 0, 0);
;     p1 = __builtin_amdgcn_mfma_f32_32x32x16_bf16(b1, qv, p1, 0, 0, 0); }
; }
; __device__ __forceinline__ void na_hook(f32x16& p0, f32x16& p1, int kr, int q_row, int q_col, int win_r, int win_c, const float* rpb, float inv_scale, int hi) {
;   const bool rowok = (kr >= win_r) && (kr < win_r + 8);
;   int ir = kr - q_row + 7; ir = ir < 0 ? 0 : (ir > 14 ? 14 : ir);
;   const float* rp = rpb + ir * 31;
; #pragma unroll
;   for (int r = 0; r < 16; ++r) {
;     const int kc = crow(r, hi);
;     { const bool ok = rowok && kc >= win_c && kc < win_c + 16; int ic = kc - q_col + 15; ic = ic < 0 ? 0 : (ic > 30 ? 30 : ic);
;       p0[r] = ok ? fmaf(rp[ic], inv_scale, p0[r]) : -1e30f; }
;     { const int kc2 = kc + 32; const bool ok = rowok && kc2 >= win_c && kc2 < win_c + 16; int ic = kc2 - q_col + 15; ic = ic < 0 ? 0 : (ic > 30 ? 30 : ic);
;       p1[r] = ok ? fmaf(rp[ic], inv_scale, p1[r]) : -1e30f; }
;   }
; }
.LBB0_517:
	v_cndmask_b32_e64 v116, v2, v237, s[36:37]
	v_mul_f32_e32 v127, 0xbe0293ee, v116
	v_fmamk_f32 v2, v14, 0x3e0293ee, v127
	v_fmamk_f32 v3, v96, 0x3e0293ee, v127
	v_fmamk_f32 v4, v243, 0x3e0293ee, v127
	v_fmamk_f32 v5, v244, 0x3e0293ee, v127
	v_fmamk_f32 v6, v115, 0x3e0293ee, v127
	v_fmamk_f32 v7, v245, 0x3e0293ee, v127
	v_fmamk_f32 v8, v117, 0x3e0293ee, v127
	v_fmamk_f32 v11, v118, 0x3e0293ee, v127
	v_fmamk_f32 v14, v119, 0x3e0293ee, v127
	v_fmamk_f32 v80, v120, 0x3e0293ee, v127
	v_fmamk_f32 v81, v121, 0x3e0293ee, v127
	v_fmamk_f32 v82, v122, 0x3e0293ee, v127
	v_fmamk_f32 v83, v123, 0x3e0293ee, v127
	v_fmamk_f32 v84, v124, 0x3e0293ee, v127
	v_fmamk_f32 v85, v125, 0x3e0293ee, v127
	v_fmamk_f32 v86, v126, 0x3e0293ee, v127
	v_fmamk_f32 v124, v0, 0x3e0293ee, v127
	v_exp_f32_e32 v121, v2
	v_exp_f32_e32 v123, v3
	v_exp_f32_e32 v12, v4
	v_exp_f32_e32 v122, v5
	v_exp_f32_e32 v10, v6
	v_exp_f32_e32 v13, v7
	v_exp_f32_e32 v9, v8
	v_exp_f32_e32 v11, v11
	v_exp_f32_e32 v6, v14
	v_exp_f32_e32 v8, v80
	v_exp_f32_e32 v4, v81
	v_exp_f32_e32 v7, v82
	v_exp_f32_e32 v2, v83
	v_exp_f32_e32 v5, v84
	v_exp_f32_e32 v0, v85
	v_exp_f32_e32 v3, v86
	v_fmamk_f32 v125, v15, 0x3e0293ee, v127
	v_fmamk_f32 v126, v97, 0x3e0293ee, v127
	v_fmamk_f32 v130, v98, 0x3e0293ee, v127
	v_fmamk_f32 v131, v99, 0x3e0293ee, v127
	v_fmamk_f32 v132, v100, 0x3e0293ee, v127
	v_fmamk_f32 v133, v101, 0x3e0293ee, v127
	v_fmamk_f32 v134, v102, 0x3e0293ee, v127
	v_fmamk_f32 v135, v103, 0x3e0293ee, v127
	v_fmamk_f32 v136, v104, 0x3e0293ee, v127
	v_fmamk_f32 v137, v105, 0x3e0293ee, v127
	v_fmamk_f32 v138, v106, 0x3e0293ee, v127
	v_fmamk_f32 v139, v107, 0x3e0293ee, v127
	v_fmamk_f32 v140, v108, 0x3e0293ee, v127
	v_fmamk_f32 v141, v109, 0x3e0293ee, v127
	v_fmac_f32_e32 v127, 0x3e0293ee, v110
	s_mov_b64 s[52:53], s[54:55]
	s_waitcnt lgkmcnt(0)
	s_barrier
	ds_write_b128 v152, v[168:171]
	ds_write_b128 v153, v[194:197]
	ds_read_b128 v[80:83], v147
	ds_read_b128 v[84:87], v158 offset:32768
	ds_read_b128 v[88:91], v158 offset:40960
	ds_read_b128 v[142:145], v147 offset:1024
	ds_read_b128 v[244:247], v159 offset:32768
	ds_read_b128 v[164:167], v159 offset:40960
	s_add_i32 s50, s50, -1
	v_readlane_b32 s36, v255, 32
	s_waitcnt lgkmcnt(4)
	v_mfma_f32_32x32x16_bf16 v[96:111], v[84:87], v[80:83], 0
	s_cmp_lt_u32 s50, s36
	v_readlane_b32 s48, v255, 33
	s_cselect_b64 s[36:37], -1, 0
	s_cmp_ge_u32 s50, s48
	s_cselect_b64 s[48:49], -1, 0
	s_add_i32 s51, s51, -1
	s_or_b64 s[36:37], s[36:37], s[48:49]
	s_waitcnt lgkmcnt(3)
	v_mfma_f32_32x32x16_bf16 v[80:95], v[88:91], v[80:83], 0
	ds_read_b128 v[168:171], v147 offset:2048
	ds_read_b128 v[172:175], v160 offset:32768
	ds_read_b128 v[194:197], v160 offset:40960
	v_med3_i32 v14, s51, -7, 7
	s_movk_i32 s48, 0x7c
	v_mul_lo_u32 v14, v14, s48
	v_readlane_b32 s48, v255, 50
	v_add_u32_e32 v14, 0, v14
	v_readlane_b32 s49, v255, 51
	s_nor_b64 s[50:51], s[48:49], s[36:37]
	s_waitcnt lgkmcnt(4)
	v_mfma_f32_32x32x16_bf16 v[96:111], v[244:247], v[142:145], v[96:111]
	v_mov_b32_e32 v115, 0xf149f2ca
	s_waitcnt lgkmcnt(3)
	v_mfma_f32_32x32x16_bf16 v[80:95], v[164:167], v[142:145], v[80:95]
	ds_read_b128 v[142:145], v147 offset:3072
	ds_read_b128 v[164:167], v161 offset:32768
	ds_read_b128 v[244:247], v161 offset:40960
	s_waitcnt lgkmcnt(4)
	v_mfma_f32_32x32x16_bf16 v[96:111], v[172:175], v[168:171], v[96:111]
	s_waitcnt lgkmcnt(3)
	v_mfma_f32_32x32x16_bf16 v[80:95], v[194:197], v[168:171], v[80:95]
	ds_read_b128 v[168:171], v147 offset:4096
	ds_read_b128 v[172:175], v176 offset:32768
	ds_read_b128 v[194:197], v176 offset:40960
	s_waitcnt lgkmcnt(4)
	v_mfma_f32_32x32x16_bf16 v[96:111], v[164:167], v[142:145], v[96:111]
	s_waitcnt lgkmcnt(3)
	v_mfma_f32_32x32x16_bf16 v[80:95], v[244:247], v[142:145], v[80:95]
	ds_read_b128 v[142:145], v147 offset:5120
	ds_read_b128 v[164:167], v177 offset:32768
	ds_read_b128 v[244:247], v177 offset:40960
	s_waitcnt lgkmcnt(4)
	v_mfma_f32_32x32x16_bf16 v[96:111], v[172:175], v[168:171], v[96:111]
	s_waitcnt lgkmcnt(3)
	v_mfma_f32_32x32x16_bf16 v[80:95], v[194:197], v[168:171], v[80:95]
	ds_read_b128 v[168:171], v147 offset:6144
	ds_read_b128 v[172:175], v207 offset:32768
	ds_read_b128 v[194:197], v207 offset:40960
	s_waitcnt lgkmcnt(4)
	v_mfma_f32_32x32x16_bf16 v[96:111], v[164:167], v[142:145], v[96:111]
	s_waitcnt lgkmcnt(3)
	v_mfma_f32_32x32x16_bf16 v[80:95], v[244:247], v[142:145], v[80:95]
	ds_read_b128 v[142:145], v147 offset:7168
	ds_read_b128 v[164:167], v208 offset:32768
	ds_read_b128 v[244:247], v208 offset:40960
	s_waitcnt lgkmcnt(4)
	v_mfma_f32_32x32x16_bf16 v[96:111], v[172:175], v[168:171], v[96:111]
	s_waitcnt lgkmcnt(3)
	v_mfma_f32_32x32x16_bf16 v[80:95], v[194:197], v[168:171], v[80:95]
	s_waitcnt lgkmcnt(1)
	v_mfma_f32_32x32x16_bf16 v[96:111], v[164:167], v[142:145], v[96:111]
	s_waitcnt lgkmcnt(0)
	v_mfma_f32_32x32x16_bf16 v[80:95], v[244:247], v[142:145], v[80:95]
	v_add_u32_e32 v142, 0x10800, v14
	v_mov_b32_e32 v14, 0xf149f2ca
	v_lshl_add_u32 v162, v242, 2, v142
	ds_read_b32 v162, v162 offset:928
	v_lshl_add_u32 v178, v209, 2, v142
	ds_read_b32 v178, v178 offset:928
	v_lshl_add_u32 v179, v210, 2, v142
	ds_read_b32 v179, v179 offset:928
	v_lshl_add_u32 v180, v211, 2, v142
	ds_read_b32 v180, v180 offset:928
	v_lshl_add_u32 v201, v212, 2, v142
	ds_read_b32 v201, v201 offset:928
	v_lshl_add_u32 v202, v213, 2, v142
	ds_read_b32 v202, v202 offset:928
	v_lshl_add_u32 v168, v214, 2, v142
	ds_read_b32 v168, v168 offset:928
	v_lshl_add_u32 v169, v215, 2, v142
	ds_read_b32 v169, v169 offset:928
	v_lshl_add_u32 v170, v216, 2, v142
	ds_read_b32 v170, v170 offset:928
	v_lshl_add_u32 v171, v217, 2, v142
	ds_read_b32 v171, v171 offset:928
	v_lshl_add_u32 v190, v218, 2, v142
	ds_read_b32 v190, v190 offset:928
	v_lshl_add_u32 v191, v219, 2, v142
	ds_read_b32 v191, v191 offset:928
	v_lshl_add_u32 v193, v220, 2, v142
	ds_read_b32 v193, v193 offset:928
	v_lshl_add_u32 v194, v221, 2, v142
	ds_read_b32 v194, v194 offset:928
	v_lshl_add_u32 v195, v222, 2, v142
	ds_read_b32 v195, v195 offset:928
	v_lshl_add_u32 v196, v223, 2, v142
	ds_read_b32 v196, v196 offset:928
	s_waitcnt lgkmcnt(0)
	v_fmamk_f32 v162, v162, 0x413504f3, v96
	v_cndmask_b32_e64 v115, v155, v162, s[50:51]
; __device__ __forceinline__ int crow(int r, int hi) { return (r & 3) + 8 * (r >> 2) + 4 * hi; }
; __device__ __forceinline__ void na_hook(f32x16& p0, f32x16& p1, int kr, int q_row, int q_col, int win_r, int win_c, const float* rpb, float inv_scale, int hi) {
;   const bool rowok = (kr >= win_r) && (kr < win_r + 8);
;   int ir = kr - q_row + 7; ir = ir < 0 ? 0 : (ir > 14 ? 14 : ir);
;   const float* rp = rpb + ir * 31;
; #pragma unroll
;   for (int r = 0; r < 16; ++r) {
;     const int kc = crow(r, hi);
;     { const bool ok = rowok && kc >= win_c && kc < win_c + 16; int ic = kc - q_col + 15; ic = ic < 0 ? 0 : (ic > 30 ? 30 : ic);
;       p0[r] = ok ? fmaf(rp[ic], inv_scale, p0[r]) : -1e30f; }
;     { const int kc2 = kc + 32; const bool ok = rowok && kc2 >= win_c && kc2 < win_c + 16; int ic = kc2 - q_col + 15; ic = ic < 0 ? 0 : (ic > 30 ? 30 : ic);
;       p1[r] = ok ? fmaf(rp[ic], inv_scale, p1[r]) : -1e30f; }
;   }
; }
.LBB0_519:
	s_xor_b64 vcc, s[36:37], -1
	v_readlane_b32 s50, v255, 52
	s_and_b64 s[48:49], vcc, s[52:53]
	v_readlane_b32 s51, v255, 53
	s_and_b64 s[50:51], s[48:49], s[50:51]
	v_fmamk_f32 v178, v178, 0x413504f3, v80
	v_cndmask_b32_e64 v14, v155, v178, s[50:51]
.LBB0_521:
	v_readlane_b32 s48, v255, 54
	v_readlane_b32 s49, v255, 55
	s_nor_b64 s[50:51], s[48:49], s[36:37]
	v_mov_b32_e32 v15, 0xf149f2ca
	v_mov_b32_e32 v117, 0xf149f2ca
	v_fmamk_f32 v179, v179, 0x413504f3, v97
	v_cndmask_b32_e64 v117, v155, v179, s[50:51]
.LBB0_523:
	v_readlane_b32 s48, v255, 56
	v_readlane_b32 s49, v255, 57
	s_and_b64 s[48:49], vcc, s[48:49]
	s_and_b64 s[50:51], s[48:49], s[56:57]
	v_fmamk_f32 v180, v180, 0x413504f3, v81
	v_cndmask_b32_e64 v15, v155, v180, s[50:51]
.LBB0_525:
	s_nor_b64 s[50:51], s[58:59], s[36:37]
	v_mov_b32_e32 v96, 0xf149f2ca
	v_mov_b32_e32 v118, 0xf149f2ca
	v_fmamk_f32 v201, v201, 0x413504f3, v98
	v_cndmask_b32_e64 v118, v155, v201, s[50:51]
.LBB0_527:
	s_and_b64 s[48:49], vcc, s[60:61]
	s_and_b64 s[50:51], s[48:49], s[62:63]
	v_fmamk_f32 v202, v202, 0x413504f3, v82
	v_cndmask_b32_e64 v96, v155, v202, s[50:51]
.LBB0_529:
	s_nor_b64 s[50:51], s[64:65], s[36:37]
	v_mov_b32_e32 v97, 0xf149f2ca
	v_mov_b32_e32 v119, 0xf149f2ca
	v_fmamk_f32 v168, v168, 0x413504f3, v99
	v_cndmask_b32_e64 v119, v155, v168, s[50:51]
.LBB0_531:
	s_and_b64 s[48:49], vcc, s[66:67]
	s_and_b64 s[50:51], s[48:49], s[68:69]
	v_fmamk_f32 v169, v169, 0x413504f3, v83
	v_cndmask_b32_e64 v97, v155, v169, s[50:51]
.LBB0_533:
	s_nor_b64 s[50:51], s[70:71], s[36:37]
	v_mov_b32_e32 v98, 0xf149f2ca
	v_mov_b32_e32 v120, 0xf149f2ca
	v_fmamk_f32 v170, v170, 0x413504f3, v100
	v_cndmask_b32_e64 v120, v155, v170, s[50:51]
.LBB0_535:
	s_and_b64 s[48:49], vcc, s[72:73]
	s_and_b64 s[50:51], s[48:49], s[74:75]
	v_fmamk_f32 v171, v171, 0x413504f3, v84
	v_cndmask_b32_e64 v98, v155, v171, s[50:51]
.LBB0_537:
	s_nor_b64 s[50:51], s[76:77], s[36:37]
	v_mov_b32_e32 v99, 0xf149f2ca
	v_mov_b32_e32 v100, 0xf149f2ca
	v_fmamk_f32 v190, v190, 0x413504f3, v101
	v_cndmask_b32_e64 v100, v155, v190, s[50:51]
.LBB0_539:
	s_and_b64 s[48:49], vcc, s[78:79]
	s_and_b64 s[50:51], s[48:49], s[80:81]
	v_fmamk_f32 v191, v191, 0x413504f3, v85
	v_cndmask_b32_e64 v99, v155, v191, s[50:51]
.LBB0_541:
	s_nor_b64 s[50:51], s[82:83], s[36:37]
	v_mov_b32_e32 v84, 0xf149f2ca
	v_mov_b32_e32 v101, 0xf149f2ca
	v_fmamk_f32 v193, v193, 0x413504f3, v102
	v_cndmask_b32_e64 v101, v155, v193, s[50:51]
.LBB0_543:
	s_and_b64 s[48:49], vcc, s[84:85]
	s_and_b64 s[50:51], s[48:49], s[86:87]
	v_fmamk_f32 v194, v194, 0x413504f3, v86
	v_cndmask_b32_e64 v84, v155, v194, s[50:51]
.LBB0_545:
	s_nor_b64 s[50:51], s[88:89], s[36:37]
	v_mov_b32_e32 v85, 0xf149f2ca
	v_mov_b32_e32 v102, 0xf149f2ca
	v_fmamk_f32 v195, v195, 0x413504f3, v103
	v_cndmask_b32_e64 v102, v155, v195, s[50:51]
.LBB0_547:
	s_and_b64 s[48:49], vcc, s[90:91]
	s_and_b64 s[50:51], s[48:49], s[92:93]
	v_fmamk_f32 v196, v196, 0x413504f3, v87
	v_cndmask_b32_e64 v85, v155, v196, s[50:51]
.LBB0_549:
	v_lshl_add_u32 v162, v224, 2, v142
	ds_read_b32 v162, v162 offset:928
	v_lshl_add_u32 v178, v225, 2, v142
	ds_read_b32 v178, v178 offset:928
	v_lshl_add_u32 v179, v226, 2, v142
	ds_read_b32 v179, v179 offset:928
	v_lshl_add_u32 v180, v227, 2, v142
	ds_read_b32 v180, v180 offset:928
	v_lshl_add_u32 v201, v228, 2, v142
	ds_read_b32 v201, v201 offset:928
	v_lshl_add_u32 v202, v229, 2, v142
	ds_read_b32 v202, v202 offset:928
	v_lshl_add_u32 v168, v230, 2, v142
	ds_read_b32 v168, v168 offset:928
	v_lshl_add_u32 v169, v231, 2, v142
	ds_read_b32 v169, v169 offset:928
	v_lshl_add_u32 v170, v232, 2, v142
	ds_read_b32 v170, v170 offset:928
	v_lshl_add_u32 v171, v241, 2, v142
	ds_read_b32 v171, v171 offset:1152
	v_lshl_add_u32 v190, v233, 2, v142
	ds_read_b32 v190, v190 offset:928
	v_lshl_add_u32 v191, v240, 2, v142
	ds_read_b32 v191, v191 offset:1156
	v_lshl_add_u32 v193, v234, 2, v142
	ds_read_b32 v193, v193 offset:928
	v_lshl_add_u32 v194, v238, 2, v142
	ds_read_b32 v194, v194 offset:1160
	v_lshl_add_u32 v195, v235, 2, v142
	ds_read_b32 v195, v195 offset:928
	v_lshl_add_u32 v196, v236, 2, v142
	ds_read_b32 v196, v196 offset:1164
	s_nor_b64 s[50:51], s[46:47], s[36:37]
	v_mov_b32_e32 v86, 0xf149f2ca
	v_mov_b32_e32 v103, 0xf149f2ca
	s_waitcnt lgkmcnt(0)
	v_fmamk_f32 v162, v162, 0x413504f3, v104
	v_cndmask_b32_e64 v103, v155, v162, s[50:51]
.LBB0_551:
	s_and_b64 s[50:51], vcc, s[94:95]
	v_fmamk_f32 v178, v178, 0x413504f3, v88
	v_cndmask_b32_e64 v86, v155, v178, s[50:51]
.LBB0_553:
	s_or_b64 s[48:49], s[96:97], s[36:37]
	s_nor_b64 s[50:51], s[48:49], s[2:3]
	v_mov_b32_e32 v87, 0xf149f2ca
	v_mov_b32_e32 v104, 0xf149f2ca
	v_fmamk_f32 v179, v179, 0x413504f3, v105
	v_cndmask_b32_e64 v104, v155, v179, s[50:51]
.LBB0_555:
	s_and_b64 s[50:51], vcc, s[4:5]
	v_fmamk_f32 v180, v180, 0x413504f3, v89
	v_cndmask_b32_e64 v87, v155, v180, s[50:51]
.LBB0_557:
	s_or_b64 s[48:49], s[6:7], s[36:37]
	s_nor_b64 s[50:51], s[48:49], s[8:9]
	v_mov_b32_e32 v88, 0xf149f2ca
	v_mov_b32_e32 v105, 0xf149f2ca
	v_fmamk_f32 v201, v201, 0x413504f3, v106
	v_cndmask_b32_e64 v105, v155, v201, s[50:51]
.LBB0_559:
	s_and_b64 s[50:51], vcc, s[10:11]
	v_fmamk_f32 v202, v202, 0x413504f3, v90
	v_cndmask_b32_e64 v88, v155, v202, s[50:51]
.LBB0_561:
	s_or_b64 s[48:49], s[12:13], s[36:37]
	s_nor_b64 s[50:51], s[48:49], s[14:15]
	v_mov_b32_e32 v89, 0xf149f2ca
	v_mov_b32_e32 v106, 0xf149f2ca
	v_fmamk_f32 v168, v168, 0x413504f3, v107
	v_cndmask_b32_e64 v106, v155, v168, s[50:51]
.LBB0_563:
	s_and_b64 s[50:51], vcc, s[16:17]
	v_fmamk_f32 v169, v169, 0x413504f3, v91
	v_cndmask_b32_e64 v89, v155, v169, s[50:51]
.LBB0_565:
	s_or_b64 s[48:49], s[18:19], s[36:37]
	s_nor_b64 s[50:51], s[48:49], s[20:21]
	v_mov_b32_e32 v90, 0xf149f2ca
	v_mov_b32_e32 v107, 0xf149f2ca
	v_fmamk_f32 v170, v170, 0x413504f3, v108
	v_cndmask_b32_e64 v107, v155, v170, s[50:51]
.LBB0_567:
	s_nor_b64 s[50:51], s[36:37], s[22:23]
	v_fmamk_f32 v171, v171, 0x413504f3, v92
	v_cndmask_b32_e64 v90, v155, v171, s[50:51]
.LBB0_569:
	s_or_b64 s[48:49], s[24:25], s[36:37]
	s_nor_b64 s[50:51], s[48:49], s[26:27]
	v_mov_b32_e32 v91, 0xf149f2ca
	v_mov_b32_e32 v108, 0xf149f2ca
	v_fmamk_f32 v190, v190, 0x413504f3, v109
	v_cndmask_b32_e64 v108, v155, v190, s[50:51]
.LBB0_571:
	s_nor_b64 s[50:51], s[36:37], s[28:29]
	v_fmamk_f32 v191, v191, 0x413504f3, v93
	v_cndmask_b32_e64 v91, v155, v191, s[50:51]
.LBB0_573:
	s_or_b64 s[48:49], s[30:31], s[36:37]
	s_nor_b64 s[50:51], s[48:49], s[34:35]
	v_mov_b32_e32 v92, 0xf149f2ca
	v_mov_b32_e32 v109, 0xf149f2ca
	v_fmamk_f32 v193, v193, 0x413504f3, v110
	v_cndmask_b32_e64 v109, v155, v193, s[50:51]
.LBB0_575:
	s_nor_b64 s[50:51], s[36:37], s[42:43]
	v_fmamk_f32 v194, v194, 0x413504f3, v94
	v_cndmask_b32_e64 v92, v155, v194, s[50:51]
.LBB0_577:
	s_or_b64 s[48:49], s[0:1], s[36:37]
	s_nor_b64 s[48:49], s[48:49], s[40:41]
	v_mov_b32_e32 v93, 0xf149f2ca
	v_mov_b32_e32 v94, 0xf149f2ca
	s_and_saveexec_b64 vcc, s[48:49]
	s_cbranch_execz .LBB0_579
	v_fmac_f32_e32 v111, 0x413504f3, v195
	v_mov_b32_e32 v94, v111
